# phase0 convert: prefetch wait moved after store phase (was vmcnt(0) right after issuing next tile loads); sel_head epilogue loads batched
# speedup vs baseline: 1.0142x; 1.0142x over previous
; __device__ __forceinline__ unsigned pk2(float lo, float hi) { f32x2_t v = {lo, hi}; bf16x2_t b = __builtin_convertvector(v, bf16x2_t); return __builtin_bit_cast(unsigned, b); }
; __device__ __forceinline__ void sel_head_item(const Args& a, int it, unsigned char* lds) {
;     ...
;     {
;         const int t = b * SEQ + tokbase + fr;
;         const float sc = GT[(size_t)t * 32 + g * 9 + r * 3 + 1] / fmaxf(lrow, 1e-30f);
;         f32x4 pv[8];
; #pragma unroll
;         for (int dt = 0; dt < 8; ++dt) {
;             const size_t o = (size_t)t * 768 + (g * 3 + r) * 128 + dt * 16 + 4 * fq;
;             pv[dt] = __builtin_nontemporal_load((const f32x4*)(On + o)) + __builtin_nontemporal_load((const f32x4*)(Oc2 + o));
;         }
; #pragma unroll
;         for (int dt = 0; dt < 8; ++dt) {
;             const f32x4 v = pv[dt] + O[dt] * sc;
;             u32x2 pk; pk.x = pk2(v.x, v.y); pk.y = pk2(v.z, v.w);
;             *(u32x2*)(Y + (size_t)t * DM + (g * 3 + r) * 128 + dt * 16 + 4 * fq) = pk;
;         }
.LBB0_194:
	v_and_b32_e32 v33, 64, v226
	v_xor_b32_e32 v32, 16, v226
	v_add_u32_e32 v33, 64, v33
	v_cmp_lt_i32_e32 vcc, v32, v33
	v_xor_b32_e32 v34, 32, v226
	s_add_u32 s26, s82, s26
	v_cndmask_b32_e32 v32, v226, v32, vcc
	v_lshlrev_b32_e32 v32, 2, v32
	ds_bpermute_b32 v32, v32, v167
	v_cmp_lt_i32_e32 vcc, v34, v33
	s_addc_u32 s27, s83, s27
	s_add_u32 s24, s80, s24
	v_cndmask_b32_e32 v33, v226, v34, vcc
	s_waitcnt lgkmcnt(0)
	v_add_f32_e32 v32, v167, v32
	v_lshlrev_b32_e32 v33, 2, v33
	ds_bpermute_b32 v33, v33, v32
	s_addc_u32 s25, s81, s25
	s_add_u32 s22, s74, s22
	s_addc_u32 s23, s75, s23
	v_ashrrev_i32_e32 v145, 31, v144
	s_add_u32 s20, s38, s20
	s_addc_u32 s21, s39, s21
	s_waitcnt lgkmcnt(0)
	v_add_f32_e32 v34, v32, v33
	v_lshlrev_b64 v[32:33], 7, v[144:145]
	s_mul_i32 s14, s14, 3
	v_lshl_add_u64 v[32:33], s[20:21], 0, v[32:33]
	s_mul_i32 s92, s13, 36
	s_ashr_i32 s15, s14, 31
	v_lshl_add_u64 v[32:33], v[32:33], 0, s[92:93]
	s_waitcnt vmcnt(0)
	v_lshl_add_u64 v[32:33], s[14:15], 2, v[32:33]
	global_load_dword v70, v[32:33], off offset:4
	v_lshl_add_u64 v[32:33], v[146:147], 0, s[2:3]
	v_lshl_or_b32 v32, v164, 2, v32
	v_lshlrev_b64 v[36:37], 2, v[32:33]
	s_waitcnt vmcnt(0)
	v_lshl_add_u64 v[58:59], s[22:23], 0, v[36:37]
	v_lshl_add_u64 v[66:67], s[24:25], 0, v[36:37]
	v_max_f32_e32 v71, 0xda24260, v34
	global_load_dwordx4 v[72:75], v[58:59], off nt
	global_load_dwordx4 v[76:79], v[66:67], off nt
	global_load_dwordx4 v[80:83], v[58:59], off offset:64 nt
	global_load_dwordx4 v[84:87], v[66:67], off offset:64 nt
	global_load_dwordx4 v[88:91], v[58:59], off offset:128 nt
	global_load_dwordx4 v[92:95], v[66:67], off offset:128 nt
	global_load_dwordx4 v[96:99], v[58:59], off offset:192 nt
	global_load_dwordx4 v[100:103], v[66:67], off offset:192 nt
	global_load_dwordx4 v[104:107], v[58:59], off offset:256 nt
	global_load_dwordx4 v[108:111], v[66:67], off offset:256 nt
	global_load_dwordx4 v[112:115], v[58:59], off offset:320 nt
	global_load_dwordx4 v[116:119], v[66:67], off offset:320 nt
	global_load_dwordx4 v[120:123], v[58:59], off offset:384 nt
	global_load_dwordx4 v[124:127], v[66:67], off offset:384 nt
	global_load_dwordx4 v[128:131], v[58:59], off offset:448 nt
	global_load_dwordx4 v[132:135], v[66:67], off offset:448 nt
	s_nop 0
	s_nop 0
	v_lshlrev_b32_e32 v214, 3, v164
	s_nop 0
	s_waitcnt vmcnt(14)
	v_pk_add_f32 v[62:63], v[74:75], v[78:79]
	v_pk_add_f32 v[64:65], v[72:73], v[76:77]
	s_nop 0
	s_nop 0
	s_nop 0
	s_waitcnt vmcnt(12)
	v_pk_add_f32 v[60:61], v[82:83], v[86:87]
	v_pk_add_f32 v[56:57], v[80:81], v[84:85]
	s_nop 0
	s_nop 0
	s_nop 0
	s_waitcnt vmcnt(10)
	v_pk_add_f32 v[54:55], v[90:91], v[94:95]
	v_pk_add_f32 v[52:53], v[88:89], v[92:93]
	s_nop 0
	s_nop 0
	s_nop 0
	s_waitcnt vmcnt(8)
	v_pk_add_f32 v[50:51], v[98:99], v[102:103]
	v_pk_add_f32 v[48:49], v[96:97], v[100:101]
	s_nop 0
	s_nop 0
	s_nop 0
	s_waitcnt vmcnt(6)
	v_pk_add_f32 v[34:35], v[106:107], v[110:111]
	v_pk_add_f32 v[32:33], v[104:105], v[108:109]
	s_nop 0
	s_nop 0
	s_nop 0
	s_waitcnt vmcnt(4)
	v_pk_add_f32 v[38:39], v[114:115], v[118:119]
	v_pk_add_f32 v[36:37], v[112:113], v[116:117]
	s_nop 0
	s_nop 0
	s_nop 0
	s_waitcnt vmcnt(2)
	v_pk_add_f32 v[42:43], v[122:123], v[126:127]
	v_pk_add_f32 v[40:41], v[120:121], v[124:125]
	s_nop 0
	s_nop 0
	s_nop 0
	v_div_scale_f32 v58, s[14:15], v71, v71, v70
	v_rcp_f32_e32 v59, v58
	s_nop 0
	s_waitcnt vmcnt(0)
	v_pk_add_f32 v[44:45], v[128:129], v[132:133]
	v_fma_f32 v66, -v58, v59, 1.0
	v_fmac_f32_e32 v59, v66, v59
	v_div_scale_f32 v66, vcc, v70, v71, v70
	v_mul_f32_e32 v67, v66, v59
	v_pk_add_f32 v[46:47], v[130:131], v[134:135]
	v_fma_f32 v68, -v58, v67, v66
	v_fmac_f32_e32 v67, v68, v59
	v_fma_f32 v58, -v58, v67, v66
	v_div_fmas_f32 v58, v58, v59, v67
	v_lshlrev_b64 v[66:67], 12, v[144:145]
	v_div_fixup_f32 v58, v58, v71, v70
	v_lshl_add_u64 v[66:67], s[26:27], 0, v[66:67]
	v_lshl_add_u64 v[66:67], s[2:3], 1, v[66:67]
	v_pk_fma_f32 v[2:3], v[2:3], v[58:59], v[62:63] op_sel_hi:[1,0,1]
	v_pk_fma_f32 v[0:1], v[0:1], v[58:59], v[64:65] op_sel_hi:[1,0,1]
	v_lshl_add_u64 v[66:67], v[66:67], 0, v[214:215]
	v_cvt_pk_bf16_f32 v0, v0, v1
	v_cvt_pk_bf16_f32 v1, v2, v3
	global_store_dwordx2 v[66:67], v[0:1], off
	v_pk_fma_f32 v[0:1], v[6:7], v[58:59], v[60:61] op_sel_hi:[1,0,1]
	v_pk_fma_f32 v[2:3], v[4:5], v[58:59], v[56:57] op_sel_hi:[1,0,1]
	s_nop 0
	v_cvt_pk_bf16_f32 v2, v2, v3
	v_cvt_pk_bf16_f32 v3, v0, v1
	global_store_dwordx2 v[66:67], v[2:3], off offset:32
	v_pk_fma_f32 v[0:1], v[10:11], v[58:59], v[54:55] op_sel_hi:[1,0,1]
	v_pk_fma_f32 v[2:3], v[8:9], v[58:59], v[52:53] op_sel_hi:[1,0,1]
	s_nop 0
	v_cvt_pk_bf16_f32 v2, v2, v3
	v_cvt_pk_bf16_f32 v3, v0, v1
	global_store_dwordx2 v[66:67], v[2:3], off offset:64
	v_pk_fma_f32 v[0:1], v[14:15], v[58:59], v[50:51] op_sel_hi:[1,0,1]
	v_pk_fma_f32 v[2:3], v[12:13], v[58:59], v[48:49] op_sel_hi:[1,0,1]
	s_nop 0
	v_cvt_pk_bf16_f32 v2, v2, v3
	v_cvt_pk_bf16_f32 v3, v0, v1
	global_store_dwordx2 v[66:67], v[2:3], off offset:96
	v_pk_fma_f32 v[0:1], v[18:19], v[58:59], v[34:35] op_sel_hi:[1,0,1]
	v_pk_fma_f32 v[2:3], v[16:17], v[58:59], v[32:33] op_sel_hi:[1,0,1]
	s_nop 0
	v_cvt_pk_bf16_f32 v2, v2, v3
	v_cvt_pk_bf16_f32 v3, v0, v1
	global_store_dwordx2 v[66:67], v[2:3], off offset:128
	v_pk_fma_f32 v[0:1], v[22:23], v[58:59], v[38:39] op_sel_hi:[1,0,1]
	v_pk_fma_f32 v[2:3], v[20:21], v[58:59], v[36:37] op_sel_hi:[1,0,1]
	s_nop 0
	v_cvt_pk_bf16_f32 v2, v2, v3
	v_cvt_pk_bf16_f32 v3, v0, v1
	global_store_dwordx2 v[66:67], v[2:3], off offset:160
	v_pk_fma_f32 v[0:1], v[26:27], v[58:59], v[42:43] op_sel_hi:[1,0,1]
	v_pk_fma_f32 v[2:3], v[24:25], v[58:59], v[40:41] op_sel_hi:[1,0,1]
	s_nop 0
	v_cvt_pk_bf16_f32 v2, v2, v3
	v_cvt_pk_bf16_f32 v3, v0, v1
	global_store_dwordx2 v[66:67], v[2:3], off offset:192
	v_pk_fma_f32 v[0:1], v[30:31], v[58:59], v[46:47] op_sel_hi:[1,0,1]
	v_pk_fma_f32 v[2:3], v[28:29], v[58:59], v[44:45] op_sel_hi:[1,0,1]
	s_nop 0
	v_cvt_pk_bf16_f32 v2, v2, v3
	v_cvt_pk_bf16_f32 v3, v0, v1
	global_store_dwordx2 v[66:67], v[2:3], off offset:224

; __device__ __forceinline__ void lds_barrier() { asm volatile("s_waitcnt lgkmcnt(0)\n\ts_barrier" ::: "memory"); }
; __device__ __forceinline__ void conv_store(const Args& a, const ConvDesc& d, const f32x4 (&v)[4], float* scr, int tid) {
;     const int nbn = (d.N + 127) / 128, kb = d.r / nbn, nb = d.r % nbn, k0 = kb * 64, n0 = nb * 128;
;     lds_barrier();
; #pragma unroll
;     for (int i = 0; i < 4; ++i) {
;         const int idx = i * 512 + tid, kk = idx >> 5, n4 = (idx & 31) * 4;
;         scr[(n4 + 0) * 65 + kk] = v[i].x; scr[(n4 + 1) * 65 + kk] = v[i].y; scr[(n4 + 2) * 65 + kk] = v[i].z; scr[(n4 + 3) * 65 + kk] = v[i].w;
;     }
;     lds_barrier();
; #pragma unroll
;     for (int h = 0; h < 2; ++h) {
;         const int nn = h * 64 + (tid >> 3), kc = (tid & 7) * 8;
.LBB0_936:
	s_andn2_b64 vcc, exec, s[18:19]
	s_cbranch_vccnz .LBB0_1053
	v_lshlrev_b32_e32 v16, 2, v18
	v_and_b32_e32 v32, 0x7c, v16
	v_add_u32_e32 v16, 0x200, v18
	v_ashrrev_i32_e32 v35, 5, v16
	v_add_u32_e32 v16, 0x400, v18
	v_ashrrev_i32_e32 v38, 5, v16
	v_add_u32_e32 v16, 0x600, v18
	s_movk_i32 s24, 0x104
	v_ashrrev_i32_e32 v33, 5, v18
	v_ashrrev_i32_e32 v39, 5, v16
	v_mad_u32_u24 v16, v32, s24, 0
	v_readlane_b32 s14, v255, 28
	v_lshl_add_u32 v40, v33, 2, v16
	v_lshl_add_u32 v41, v35, 2, v16
	v_lshl_add_u32 v42, v38, 2, v16
	v_lshl_add_u32 v43, v39, 2, v16
	v_ashrrev_i32_e32 v44, 3, v18
	v_lshlrev_b32_e32 v16, 3, v18
	v_readlane_b32 s15, v255, 29
	v_and_b32_e32 v34, 56, v16
	v_add_u32_e32 v46, 64, v44
	s_ashr_i32 s15, s14, 31
	v_lshl_add_u32 v16, v34, 2, 0
	v_mul_lo_u32 v17, v44, s24
	v_and_b32_e32 v45, 0x7f, v44
	v_and_b32_e32 v47, 0x7f, v46
	s_lshl_b64 s[18:19], s[14:15], 14
	s_lshl_b64 s[20:21], s[14:15], 19
	s_lshl_b64 s[22:23], s[14:15], 22
	s_mul_hi_i32 s15, s14, 0xe8e000
	s_mul_i32 s14, s14, 0xe8e000
	v_or_b32_e32 v48, 0x80, v45
	v_or_b32_e32 v49, 0x80, v47
	v_add_u32_e32 v50, v16, v17
	s_waitcnt vmcnt(0)
	s_branch .LBB0_941

; #define TIDX opaque_tid()
; __device__ __forceinline__ void conv_decode(int T, int l, ConvDesc& d) {
;     constexpr int TG = 32 * 44, TD = 88 * 16, TI = 32 * 59, TO = 32 * 16, TC1 = 64 * 1, TC2 = 2 * 1;
;     const size_t lw = (size_t)l * DM * FF;
;     int r = T;
;     if (r < TG) { d = ConvDesc{2, lw, DM, FF, WS_WGU1, 1, r}; return; } r -= TG;
;     if (r < TG) { d = ConvDesc{3, lw, DM, FF, WS_WGU1, 2, r}; return; } r -= TG;
;     if (r < TD) { d = ConvDesc{4, lw, FF, DM, WS_WD1, 0, r}; return; } r -= TD;
;     if (r < TG) { d = ConvDesc{21, lw, DM, FF, WS_WGU2, 1, r}; return; } r -= TG;
;     if (r < TG) { d = ConvDesc{22, lw, DM, FF, WS_WGU2, 2, r}; return; } r -= TG;
;     if (r < TD) { d = ConvDesc{23, lw, FF, DM, WS_WD2, 0, r}; return; } r -= TD;
;     if (r < TI) { d = ConvDesc{6, (size_t)l * DM * INW, DM, INW, WS_WIN, 3, r}; return; } r -= TI;
;     if (r < TO) { d = ConvDesc{7, (size_t)l * DM * DM, DM, DM, WS_WOUT, 0, r}; return; } r -= TO;
; __device__ __forceinline__ void conv_store(const Args& a, const ConvDesc& d, const f32x4 (&v)[4], float* scr, int tid) {
;     ...
;         if (n0 + nn < d.N) {
;             const float* sp = scr + nn * 65 + kc;
;             u32x4 o; o.x = pk2(sp[0], sp[1]); o.y = pk2(sp[2], sp[3]); o.z = pk2(sp[4], sp[5]); o.w = pk2(sp[6], sp[7]);
;             *(u32x4*)(WSP(bf16_t, d.dst_off) + (size_t)rowmap(d.mode, n0 + nn) * d.K + k0 + kc) = o;
;         }
;     }
; }
; __device__ __forceinline__ void phase_convert(const Args& a, int l, unsigned char* lds) {
;     float* scr = (float*)lds;
;     constexpr int TG = 32 * 44, TD = 88 * 16, TI = 32 * 59, TO = 32 * 16, TC1 = 64 * 1, TC2 = 2 * 1;
;     constexpr int TOTAL = 4 * TG + 2 * TD + TI + TO + 2 * TC1 + 2 * TC2;
;     {
;         const int tid = TIDX, G = GDIM;
;         int T = BIDX;
;         ConvDesc d0{}; f32x4 v[4];
;         v[0] = zero4(); v[1] = zero4(); v[2] = zero4(); v[3] = zero4();
;         if (T < TOTAL) { conv_decode(T, l, d0); conv_load(d0, v, tid); }
;         while (T < TOTAL) {
;             const int Tn = T + G;
;             ConvDesc d1{}; f32x4 vn[4];
;             vn[0] = zero4(); vn[1] = zero4(); vn[2] = zero4(); vn[3] = zero4();
;             if (Tn < TOTAL) { conv_decode(Tn, l, d1); conv_load(d1, vn, tid); }
;             conv_store(a, d0, v, scr, tid);
;             d0 = d1; v[0] = vn[0]; v[1] = vn[1]; v[2] = vn[2]; v[3] = vn[3]; T = Tn;
.LBB0_939:
	s_waitcnt lgkmcnt(0)
	s_add_u32 s16, s42, s16
	v_cvt_pk_bf16_f32 v0, v0, v1
	v_cvt_pk_bf16_f32 v1, v2, v3
	v_cvt_pk_bf16_f32 v2, v4, v5
	s_addc_u32 s17, s43, s17
	v_mad_u64_u32 v[4:5], s[42:43], v8, s57, 0
	v_cvt_pk_bf16_f32 v3, v6, v7
	v_ashrrev_i32_e32 v7, 31, v8
	v_mov_b32_e32 v6, v5
	v_mad_u64_u32 v[6:7], s[42:43], v7, s57, v[6:7]
	v_mov_b32_e32 v5, v6
	v_lshl_add_u64 v[4:5], v[4:5], 1, s[16:17]
	v_lshl_add_u64 v[4:5], s[38:39], 1, v[4:5]
	v_lshlrev_b32_e32 v214, 1, v34
	v_lshl_add_u64 v[4:5], v[4:5], 0, v[214:215]
	global_store_dwordx4 v[4:5], v[0:3], off
	s_add_u32 s101, s101, 1
.LBB0_940:
	s_or_b64 exec, exec, s[40:41]
	s_cmp_eq_u32 s101, 2
	s_cbranch_scc1 .Lcv_w2
	s_cmp_eq_u32 s101, 1
	s_cbranch_scc1 .Lcv_w1
	s_waitcnt vmcnt(0)
	s_branch .Lcv_wd
.Lcv_w2:
	s_waitcnt vmcnt(2)
	s_branch .Lcv_wd
.Lcv_w1:
	s_waitcnt vmcnt(1)
.Lcv_wd:
	s_andn2_b64 vcc, exec, s[24:25]
	s_mov_b32 s44, s60
	s_mov_b32 s59, s63
	s_mov_b64 s[16:17], s[26:27]
	s_mov_b32 s58, s62
	s_mov_b32 s57, s61
	v_mov_b32_e32 v0, v16
	v_mov_b32_e32 v1, v17
	v_mov_b32_e32 v2, v18
	v_mov_b32_e32 v3, v19
	v_mov_b32_e32 v4, v20
	v_mov_b32_e32 v5, v21
	v_mov_b32_e32 v6, v22
	v_mov_b32_e32 v7, v23
	v_mov_b32_e32 v8, v24
	v_mov_b32_e32 v9, v25
	v_mov_b32_e32 v10, v26
	v_mov_b32_e32 v11, v27
	v_mov_b32_e32 v12, v28
	v_mov_b32_e32 v13, v29
	v_mov_b32_e32 v14, v30
	v_mov_b32_e32 v15, v31
	s_cbranch_vccz .LBB0_1052
.LBB0_941:
	s_mov_b32 s101, 0
	s_add_i32 s56, s56, s13
	s_cmpk_gt_i32 s56, 0x2ae3
	s_mov_b32 s38, 0
	s_mov_b32 s39, 0
	s_mov_b32 s40, 0
	s_mov_b32 s41, 0
	s_cselect_b64 s[24:25], -1, 0
	s_mov_b32 s60, 0
	s_mov_b64 s[26:27], 0
	s_and_b64 vcc, exec, s[24:25]
	v_mov_b32_e32 v31, s41
	v_mov_b32_e32 v27, s40
	v_mov_b32_e32 v23, s39
	v_mov_b32_e32 v19, s38
	v_mov_b32_e32 v30, s41
	v_mov_b32_e32 v29, s41
	v_mov_b32_e32 v28, s41
	v_mov_b32_e32 v26, s40
	v_mov_b32_e32 v25, s40
	v_mov_b32_e32 v24, s40
	v_mov_b32_e32 v22, s39
	v_mov_b32_e32 v21, s39
	v_mov_b32_e32 v20, s39
	v_mov_b32_e32 v18, s38
	v_mov_b32_e32 v17, s38
	v_mov_b32_e32 v16, s38
	s_mov_b32 s63, 0
	s_mov_b32 s62, 0
	s_mov_b32 s61, 0
	s_cbranch_vccnz .LBB0_994
	s_cmpk_lt_i32 s56, 0x580
	s_cbranch_scc1 .LBB0_956
	s_cmpk_gt_u32 s56, 0xaff
	s_mov_b64 s[42:43], -1
	s_cbranch_scc0 .LBB0_983
	s_cmpk_gt_u32 s56, 0x107f
	s_cbranch_scc0 .LBB0_980
	s_cmpk_gt_u32 s56, 0x15ff
	s_cbranch_scc0 .LBB0_977
	s_cmpk_gt_u32 s56, 0x1b7f
	s_cbranch_scc0 .LBB0_974
	s_cmpk_gt_u32 s56, 0x20ff
	s_cbranch_scc0 .LBB0_971
	s_cmpk_gt_u32 s56, 0x285f
	s_cbranch_scc0 .LBB0_968
	s_cmpk_gt_u32 s56, 0x2a5f
	s_cbranch_scc0 .LBB0_965
	s_cmpk_gt_u32 s56, 0x2a9f
	s_cbranch_scc0 .LBB0_962
	s_cmpk_gt_u32 s56, 0x2adf
	s_mov_b64 s[40:41], -1
	s_cbranch_scc0 .LBB0_959
	s_cmpk_gt_u32 s56, 0x2ae1
	s_mov_b64 s[26:27], -1
	s_cbranch_scc0 .LBB0_954
	s_add_i32 s60, s56, 0xffffd51e
	s_mov_b64 s[26:27], 0

; __device__ __forceinline__ unsigned pk2(float lo, float hi) { f32x2_t v = {lo, hi}; bf16x2_t b = __builtin_convertvector(v, bf16x2_t); return __builtin_bit_cast(unsigned, b); }
; __device__ __forceinline__ void lds_barrier() { asm volatile("s_waitcnt lgkmcnt(0)\n\ts_barrier" ::: "memory"); }
; #define WSP(T, off) ((T*)(__attribute__((address_space(1))) T*)(launder_ws(AWS, (off))))
; __device__ __forceinline__ void conv_store(const Args& a, const ConvDesc& d, const f32x4 (&v)[4], float* scr, int tid) {
;     const int nbn = (d.N + 127) / 128, kb = d.r / nbn, nb = d.r % nbn, k0 = kb * 64, n0 = nb * 128;
;     lds_barrier();
; #pragma unroll
;     for (int i = 0; i < 4; ++i) {
;         const int idx = i * 512 + tid, kk = idx >> 5, n4 = (idx & 31) * 4;
;         scr[(n4 + 0) * 65 + kk] = v[i].x; scr[(n4 + 1) * 65 + kk] = v[i].y; scr[(n4 + 2) * 65 + kk] = v[i].z; scr[(n4 + 3) * 65 + kk] = v[i].w;
;     }
;     lds_barrier();
; #pragma unroll
;     for (int h = 0; h < 2; ++h) {
;         const int nn = h * 64 + (tid >> 3), kc = (tid & 7) * 8;
;         if (n0 + nn < d.N) {
;             const float* sp = scr + nn * 65 + kc;
;             u32x4 o; o.x = pk2(sp[0], sp[1]); o.y = pk2(sp[2], sp[3]); o.z = pk2(sp[4], sp[5]); o.w = pk2(sp[6], sp[7]);
;             *(u32x4*)(WSP(bf16_t, d.dst_off) + (size_t)rowmap(d.mode, n0 + nn) * d.K + k0 + kc) = o;
.LBB0_994:
	s_add_i32 s38, s58, 0x7f
	s_lshr_b32 s39, s38, 7
	v_cvt_f32_u32_e32 v36, s39
	s_waitcnt lgkmcnt(0)
	s_barrier
	s_nop 0
	ds_write2_b32 v40, v0, v1 offset1:65
	s_sub_i32 s41, 0, s39
	v_rcp_iflag_f32_e32 v36, v36
	s_abs_i32 s40, s44
	s_ashr_i32 s38, s44, 31
	ds_write2_b32 v40, v2, v3 offset0:130 offset1:195
	ds_write2_b32 v41, v4, v5 offset1:65
	v_mul_f32_e32 v0, 0x4f7ffffe, v36
	v_cvt_u32_f32_e32 v0, v0
	ds_write2_b32 v41, v6, v7 offset0:130 offset1:195
	ds_write2_b32 v42, v8, v9 offset1:65
	ds_write2_b32 v42, v10, v11 offset0:130 offset1:195
	ds_write2_b32 v43, v12, v13 offset1:65
	ds_write2_b32 v43, v14, v15 offset0:130 offset1:195
	s_waitcnt lgkmcnt(0)
	s_barrier
	v_readfirstlane_b32 s42, v0
	s_mul_i32 s41, s41, s42
	s_mul_hi_u32 s41, s42, s41
	s_add_i32 s42, s42, s41
	s_mul_hi_u32 s41, s40, s42
	s_mul_i32 s42, s41, s39
	s_sub_i32 s40, s40, s42
	s_add_i32 s43, s41, 1
	s_sub_i32 s42, s40, s39
	s_cmp_ge_u32 s40, s39
	s_cselect_b32 s41, s43, s41
	s_cselect_b32 s40, s42, s40
	s_add_i32 s42, s41, 1
	s_cmp_ge_u32 s40, s39
	s_cselect_b32 s40, s42, s41
	s_xor_b32 s40, s40, s38
	s_sub_i32 s40, s40, s38
	s_lshl_b32 s38, s40, 6
	s_mul_i32 s40, s40, s39
	s_sub_i32 s39, s44, s40
	s_lshl_b32 s64, s39, 7
	v_add_u32_e32 v8, s64, v44
	s_ashr_i32 s39, s38, 31
	v_cmp_gt_i32_e32 vcc, s58, v8
	s_and_saveexec_b64 s[40:41], vcc
	s_cbranch_execz .LBB0_1024
	ds_read2_b32 v[0:1], v50 offset1:1
	ds_read2_b32 v[2:3], v50 offset0:2 offset1:3
	ds_read2_b32 v[4:5], v50 offset0:4 offset1:5
	ds_read2_b32 v[6:7], v50 offset0:6 offset1:7
	s_mov_b64 s[44:45], s[0:1]
	s_mov_b64 s[42:43], s[16:17]
	s_load_dwordx2 s[44:45], s[44:45], 0xd0
	s_cmp_lt_i32 s59, 1
	s_cbranch_scc1 .LBB0_1023
	s_cmp_lt_i32 s59, 2
	s_mov_b64 s[46:47], -1
	s_cbranch_scc1 .LBB0_1020
	s_cmp_lg_u32 s59, 2
	s_cbranch_scc0 .LBB0_1017
	s_movk_i32 s46, 0x8ff
	v_cmp_lt_i32_e32 vcc, s46, v8
	v_mov_b32_e32 v9, v8
	s_and_saveexec_b64 s[46:47], vcc
	s_cbranch_execz .LBB0_1016
	s_movk_i32 s48, 0x911
	v_cmp_lt_u32_e32 vcc, s48, v8
	s_and_saveexec_b64 s[48:49], vcc
	s_xor_b64 s[48:49], exec, s[48:49]
	s_cbranch_execz .LBB0_1013
	s_movk_i32 s50, 0x1091
	v_cmp_lt_u32_e32 vcc, s50, v8
	s_and_saveexec_b64 s[50:51], vcc
	s_xor_b64 s[50:51], exec, s[50:51]
	s_cbranch_execz .LBB0_1010
	s_movk_i32 s52, 0x1096
	v_cmp_lt_u32_e32 vcc, s52, v8
	s_and_saveexec_b64 s[52:53], vcc
	s_xor_b64 s[52:53], exec, s[52:53]
	s_cbranch_execz .LBB0_1007
	s_movk_i32 s54, 0x109b
	v_cmp_lt_u32_e32 vcc, s54, v8
	s_and_saveexec_b64 s[54:55], vcc
	s_xor_b64 s[54:55], exec, s[54:55]
	v_subrev_u32_e32 v9, 28, v8
	s_andn2_saveexec_b64 s[54:55], s[54:55]
	v_add_u32_e32 v9, 0xc80, v8
	s_or_b64 exec, exec, s[54:55]
	s_movk_i32 s66, 0x7f
	s_movk_i32 s67, 0x1fff

; __device__ __forceinline__ unsigned pk2(float lo, float hi) { f32x2_t v = {lo, hi}; bf16x2_t b = __builtin_convertvector(v, bf16x2_t); return __builtin_bit_cast(unsigned, b); }
; #define WSP(T, off) ((T*)(__attribute__((address_space(1))) T*)(launder_ws(AWS, (off))))
; __device__ __forceinline__ void conv_store(const Args& a, const ConvDesc& d, const f32x4 (&v)[4], float* scr, int tid) {
;     ...
;         if (n0 + nn < d.N) {
;             const float* sp = scr + nn * 65 + kc;
;             u32x4 o; o.x = pk2(sp[0], sp[1]); o.y = pk2(sp[2], sp[3]); o.z = pk2(sp[4], sp[5]); o.w = pk2(sp[6], sp[7]);
;             *(u32x4*)(WSP(bf16_t, d.dst_off) + (size_t)rowmap(d.mode, n0 + nn) * d.K + k0 + kc) = o;
.LBB0_1023:
	s_waitcnt lgkmcnt(0)
	s_add_u32 s42, s44, s42
	v_cvt_pk_bf16_f32 v0, v0, v1
	v_cvt_pk_bf16_f32 v1, v2, v3
	v_cvt_pk_bf16_f32 v2, v4, v5
	s_addc_u32 s43, s45, s43
	v_mad_u64_u32 v[4:5], s[44:45], v8, s57, 0
	v_cvt_pk_bf16_f32 v3, v6, v7
	v_ashrrev_i32_e32 v7, 31, v8
	v_mov_b32_e32 v6, v5
	v_mad_u64_u32 v[6:7], s[44:45], v7, s57, v[6:7]
	v_mov_b32_e32 v5, v6
	v_lshl_add_u64 v[4:5], v[4:5], 1, s[42:43]
	v_lshl_add_u64 v[4:5], s[38:39], 1, v[4:5]
	v_lshlrev_b32_e32 v214, 1, v34
	v_lshl_add_u64 v[4:5], v[4:5], 0, v[214:215]
	global_store_dwordx4 v[4:5], v[0:3], off
	s_add_u32 s101, s101, 1

; #define LAS3 __attribute__((address_space(3)))
; #define SEAM(ph) do { if ((ph) == a.ph_lo) grid.sync(); else xcd_barrier(xb); } while (0)
; __global__ __launch_bounds__(512, 2) void mega(Args a) {
;     extern __shared__ __attribute__((aligned(16))) unsigned char lds[];
;     cg::grid_group grid = cg::this_grid();
;     volatile LAS3 unsigned* xst = (volatile LAS3 unsigned*)(lds + DYN_LDS - 64);
;     if (threadIdx.x == 0) { xst[0] = 0u; xst[1] = 0u; }
;     __syncthreads();
;     XcdBarrier xb = xcd_barrier_post((unsigned*)(a.ws + WS_BAR), xst);
;     ...
;     int seq = 0;
;     for (int ph = a.ph_lo; ph < a.ph_hi; ++ph) {
;         if (ph < DEPTH * 12 && ((ph % 12) == 3 || (ph % 12) == 9)) continue;
;         run_phase(a, ph, lds, seq);
;     ...
;         if (PROBE_K >= 0 && ph < DEPTH * 12 && (ph % 12) == PROBE_K) for (int rep = 0; rep < PROBE_N; ++rep) { SEAM(ph); run_phase(a, ph, lds, seq, PROBE_SUB); }
;         if (PROBE_K == -2 && ph + 1 < a.ph_hi) for (int rep = 0; rep < PROBE_N; ++rep) SEAM(ph);
;     ...
;         if (ph + 1 < a.ph_hi) SEAM(ph);
;     }
; }
	.amdhsa_kernel _Z4mega4Args
		.amdhsa_group_segment_fixed_size 0
		.amdhsa_private_segment_fixed_size 0
		.amdhsa_kernarg_size 480
		.amdhsa_user_sgpr_count 2
		.amdhsa_user_sgpr_dispatch_ptr 0
		.amdhsa_user_sgpr_queue_ptr 0
		.amdhsa_user_sgpr_kernarg_segment_ptr 1
		.amdhsa_user_sgpr_dispatch_id 0
		.amdhsa_user_sgpr_kernarg_preload_length 0
		.amdhsa_user_sgpr_kernarg_preload_offset 0
		.amdhsa_user_sgpr_private_segment_size 0
		.amdhsa_uses_dynamic_stack 0
		.amdhsa_enable_private_segment 0
		.amdhsa_system_sgpr_workgroup_id_x 1
		.amdhsa_system_sgpr_workgroup_id_y 0
		.amdhsa_system_sgpr_workgroup_id_z 0
		.amdhsa_system_sgpr_workgroup_info 0
		.amdhsa_system_vgpr_workitem_id 2
		.amdhsa_next_free_vgpr 256
		.amdhsa_next_free_sgpr 102
		.amdhsa_accum_offset 256
		.amdhsa_reserve_vcc 1
		.amdhsa_float_round_mode_32 0
		.amdhsa_float_round_mode_16_64 0
		.amdhsa_float_denorm_mode_32 3
		.amdhsa_float_denorm_mode_16_64 3
		.amdhsa_dx10_clamp 1
		.amdhsa_ieee_mode 1
		.amdhsa_fp16_overflow 0
		.amdhsa_tg_split 0
		.amdhsa_exception_fp_ieee_invalid_op 0
		.amdhsa_exception_fp_denorm_src 0
		.amdhsa_exception_fp_ieee_div_zero 0
		.amdhsa_exception_fp_ieee_overflow 0
		.amdhsa_exception_fp_ieee_underflow 0
		.amdhsa_exception_fp_ieee_inexact 0
		.amdhsa_exception_int_div_zero 0
	.end_amdhsa_kernel

amdhsa.kernels:
  - .agpr_count:     0
    .args:
      - .offset:         0
        .size:           224
        .value_kind:     by_value
      - .offset:         224
        .size:           4
        .value_kind:     hidden_block_count_x
      - .offset:         228
        .size:           4
        .value_kind:     hidden_block_count_y
      - .offset:         232
        .size:           4
        .value_kind:     hidden_block_count_z
      - .offset:         236
        .size:           2
        .value_kind:     hidden_group_size_x
      - .offset:         238
        .size:           2
        .value_kind:     hidden_group_size_y
      - .offset:         240
        .size:           2
        .value_kind:     hidden_group_size_z
      - .offset:         242
        .size:           2
        .value_kind:     hidden_remainder_x
      - .offset:         244
        .size:           2
        .value_kind:     hidden_remainder_y
      - .offset:         246
        .size:           2
        .value_kind:     hidden_remainder_z
      - .offset:         264
        .size:           8
        .value_kind:     hidden_global_offset_x
      - .offset:         272
        .size:           8
        .value_kind:     hidden_global_offset_y
      - .offset:         280
        .size:           8
        .value_kind:     hidden_global_offset_z
      - .offset:         288
        .size:           2
        .value_kind:     hidden_grid_dims
      - .offset:         312
        .size:           8
        .value_kind:     hidden_multigrid_sync_arg
      - .offset:         344
        .size:           4
        .value_kind:     hidden_dynamic_lds_size
    .group_segment_fixed_size: 0
    .kernarg_segment_align: 8
    .kernarg_segment_size: 480
    .language:       OpenCL C
    .language_version:
      - 2
      - 0
    .max_flat_workgroup_size: 512
    .name:           _Z4mega4Args
    .private_segment_fixed_size: 0
    .sgpr_count:     108
    .sgpr_spill_count: 104
    .symbol:         _Z4mega4Args.kd
    .uniform_work_group_size: 1
    .uses_dynamic_stack: false
    .vgpr_count:     256
    .vgpr_spill_count: 0
    .wavefront_size: 64
